# attention units drawn from a per-workgroup LDS ticket counter instead of five/six fixed units per wave
# speedup vs baseline: 1.0002x; 1.0002x over previous
; #define LAS __attribute__((address_space(3)))
; __global__ void __launch_bounds__(NTHREADS, 2) hybrid_fwd(Args args) {
;     extern __shared__ __attribute__((aligned(16))) unsigned char lds_raw[];
;     LAS unsigned char* lds = (LAS unsigned char*)lds_raw;
;     cg::grid_group grid = cg::this_grid();
;     const int tid = threadIdx.x, lane = tid & 63, wave = __builtin_amdgcn_readfirstlane(tid >> 6);
;     const int G = gridDim.x;
;     unsigned char* ws = args.ws;
;     const int lo = args.ph_lo, hi = args.ph_hi;
;     volatile LAS unsigned* MISC = (volatile LAS unsigned*)(lds + MISC_OFF);
;     if (tid < 2) MISC[tid] = 0u;
;     __syncthreads();
;     const XcdBarrier bar = xcd_barrier_post((unsigned*)ws, MISC);
_Z10hybrid_fwd4Args:
	s_load_dwordx8 s[68:75], s[0:1], 0x60
	s_load_dwordx8 s[4:11], s[0:1], 0x40
	s_load_dword s3, s[0:1], 0x88
	s_load_dwordx2 s[84:85], s[0:1], 0x80
	s_mov_b32 s33, s2
	s_add_u32 s2, s0, 0x80
	s_waitcnt lgkmcnt(0)
	v_writelane_b32 v254, s4, 0
	v_and_b32_e32 v188, 0x3ff, v0
	v_cmp_gt_u32_e32 vcc, 4, v188
	v_writelane_b32 v254, s5, 1
	v_writelane_b32 v254, s6, 2
	v_writelane_b32 v254, s7, 3
	v_writelane_b32 v254, s8, 4
	v_writelane_b32 v254, s9, 5
	v_writelane_b32 v254, s10, 6
	v_writelane_b32 v254, s11, 7
	v_writelane_b32 v254, s3, 8
	s_addc_u32 s3, s1, 0
	v_readfirstlane_b32 s8, v188
	s_and_saveexec_b64 s[4:5], vcc
	v_lshl_add_u32 v1, v188, 2, 0
	v_add_u32_e32 v1, 0x26700, v1
	v_mov_b32_e32 v2, 0
	ds_write_b32 v1, v2
	s_or_b64 exec, exec, s[4:5]
	s_waitcnt lgkmcnt(0)
	s_barrier
	s_getreg_b32 s4, hwreg(HW_REG_XCC_ID, 0, 4)
	s_and_b32 s88, s4, 15
	v_cmp_eq_u32_e64 s[6:7], 0, v188
	s_mov_b64 s[4:5], exec
	s_nop 0
	v_writelane_b32 v254, s6, 9
	s_nop 1
	v_writelane_b32 v254, s7, 10
	s_and_b64 s[6:7], s[4:5], s[6:7]
	s_mov_b64 exec, s[6:7]
	s_cbranch_execz .LBB0_5
	s_mov_b64 s[6:7], exec
	v_mbcnt_lo_u32_b32 v1, s6, 0
	v_mbcnt_hi_u32_b32 v1, s7, v1
	v_cmp_eq_u32_e32 vcc, 0, v1
	s_and_b64 s[10:11], exec, vcc
	s_mov_b64 exec, s[10:11]
	s_cbranch_execz .LBB0_5
	s_lshl_b32 s9, s88, 8
	s_bcnt1_i32_b64 s6, s[6:7]
	v_mov_b32_e32 v1, s9
	v_mov_b32_e32 v2, s6
	global_atomic_add v1, v2, s[72:73] offset:1024

; __device__ __forceinline__ void attn_mfma(const Args& a, int u0, int ucnt, int ustride) {
;     ...
;     const int lane = threadIdx.x & 63, r32 = lane & 31, hi = lane >> 5;
;     const int kap = 16 * (r32 >> 4) + 8 * ((r32 >> 2) & 1) + 4 * ((r32 >> 3) & 1) + (r32 & 3);
;     for (int uk = 0; uk < ucnt; ++uk) { const int u = u0 + uk * ustride;
;         const int qb = u & 63, bh = u >> 6, h = bh & 15, b = bh >> 4;
;         const size_t rowq = (size_t)b * SEQ + 32 * qb + r32;
;         bf16* qp = QS + rowq * 2048 + 1024 + 64 * h;
;         const bf16* kbase = SK + ((size_t)b * SEQ + kap) * 1024 + 64 * h + 8 * hi;
;         const bf16* vbase = VT + ((size_t)bh * 64 + r32) * 2048 + 8 * hi;
; __global__ void __launch_bounds__(NTHREADS, 2) hybrid_fwd(Args args) {
;     ...
;             if ((int)blockIdx.x < 64) { hgrn_v2(args, lds, (int)blockIdx.x, 64); p0_prologue<1>(args, lds, wave, lane, 2048 + 512 + (int)blockIdx.x * NWAVES + wave, 1024); S.l0 = -1; S.l1 = -1; S.l2 = -1; }
;             else { const int idx = (int)blockIdx.x - 64;
;                 if (idx < 128) attn_mfma(args, idx * 40 + wave, 5, NWAVES); else attn_mfma(args, 5120 + (idx - 128) * 48 + wave, 6, NWAVES);
.LBB0_396:
	s_and_b64 vcc, exec, s[0:1]
	s_cbranch_vccz .LBB0_722
	s_cmp_gt_i32 s33, 63
	s_cbranch_scc0 .LBB0_406
	s_cmpk_lt_u32 s33, 0xc0
	s_cselect_b64 s[38:39], -1, 0
	s_cmpk_gt_u32 s33, 0xbf
	s_cselect_b64 s[0:1], -1, 0
	s_mov_b64 s[2:3], -1
	s_and_b64 vcc, exec, s[0:1]
	s_mul_i32 s2, s33, 48
	v_readlane_b32 s3, v254, 11
	s_add_i32 s44, s2, s3
	s_waitcnt vmcnt(0)
	v_lshlrev_b32_e32 v1, 1, v188
	v_lshrrev_b32_e32 v2, 1, v188
	v_and_b32_e32 v82, 31, v188
	v_readlane_b32 s2, v254, 22
	v_and_b32_e32 v0, 19, v188
	v_and_b32_e32 v1, 8, v1
	v_and_b32_e32 v2, 4, v2
	v_bfe_u32 v3, v188, 5, 1
	v_mov_b32_e32 v85, 0
	v_lshlrev_b32_e32 v84, 12, v82
	v_readlane_b32 s3, v254, 23
	v_or3_b32 v80, v1, v0, v2
	v_lshlrev_b32_e32 v2, 3, v3
	v_lshl_add_u64 v[0:1], s[2:3], 0, v[84:85]
	v_lshlrev_b32_e32 v84, 4, v3
	v_lshl_add_u64 v[86:87], v[0:1], 0, v[84:85]
	v_or_b32_e32 v0, 1, v2
	v_cmp_lt_u32_e64 s[4:5], v0, v82
	v_or_b32_e32 v0, 3, v2
	v_cmp_lt_u32_e64 s[6:7], v0, v82
	v_or_b32_e32 v0, 5, v2
	v_cmp_lt_u32_e64 s[10:11], v0, v82
	v_or_b32_e32 v0, 6, v2
	v_cmp_lt_u32_e64 s[14:15], v0, v82
	v_or_b32_e32 v0, 7, v2
	v_cmp_lt_u32_e64 s[16:17], v0, v82
	v_or_b32_e32 v0, 17, v2
	v_cmp_lt_u32_e64 s[18:19], v0, v82
	v_or_b32_e32 v0, 19, v2
	v_cmp_lt_u32_e64 s[22:23], v0, v82
	v_or_b32_e32 v0, 21, v2
	v_or_b32_e32 v1, 2, v2
	v_cmp_lt_u32_e64 s[26:27], v0, v82
	v_or_b32_e32 v0, 22, v2
	v_cmp_lt_u32_e64 s[8:9], v1, v82
	v_or_b32_e32 v1, 4, v2
	v_cmp_lt_u32_e64 s[30:31], v0, v82
	v_or_b32_e32 v0, 23, v2
	v_cmp_lt_u32_e64 s[12:13], v1, v82
	v_or_b32_e32 v1, 16, v2
	v_cmp_lt_u32_e64 s[34:35], v0, v82
	v_mbcnt_lo_u32_b32 v0, -1, 0
	v_cmp_lt_u32_e64 s[20:21], v1, v82
	v_or_b32_e32 v1, 18, v2
	v_mbcnt_hi_u32_b32 v0, -1, v0
	v_cmp_lt_u32_e64 s[24:25], v1, v82
	v_or_b32_e32 v1, 20, v2
	v_and_b32_e32 v4, 64, v0
	v_cmp_lt_u32_e64 s[28:29], v1, v82
	v_xor_b32_e32 v1, 32, v0
	v_add_u32_e32 v4, 64, v4
	v_cmp_lt_i32_e32 vcc, v1, v4
	s_addk_i32 s44, 0xf000
	v_cmp_lt_u32_e64 s[2:3], v2, v82
	v_cndmask_b32_e32 v0, v0, v1, vcc
	v_lshlrev_b32_e32 v81, 2, v0
	v_lshlrev_b32_e32 v0, 2, v3
	s_mov_b32 s41, 0
	v_cmp_eq_u32_e64 s[36:37], 0, v3
	v_lshlrev_b32_e32 v88, 1, v2
	v_mov_b32_e32 v89, v85
	s_mov_b32 s45, 0x8000
	v_lshlrev_b32_e32 v84, 1, v0
	s_mov_b32 s46, 0
	v_mbcnt_lo_u32_b32 v189, -1, 0
	v_mbcnt_hi_u32_b32 v189, -1, v189
	v_readlane_b32 s78, v254, 11
	v_readlane_b32 s92, v254, 22
	v_readlane_b32 s93, v254, 23
	s_nop 0
	s_lshl_b32 s78, s78, 14
	v_lshrrev_b32_e32 v206, 3, v189
	v_and_b32_e32 v207, 7, v189
	v_lshrrev_b32_e32 v208, 1, v206
	v_xor_b32_e32 v209, v207, v208
	v_xor_b32_e32 v210, 4, v209
	v_lshlrev_b32_e32 v209, 4, v209
	v_lshlrev_b32_e32 v210, 4, v210
	v_lshl_add_u32 v190, v206, 11, v209
	v_lshl_add_u32 v191, v206, 11, v210
	v_add_u32_e32 v191, 0x3c00, v191
	v_add_u32_e32 v192, 0x7800, v190
	v_add_u32_e32 v193, 0x7800, v191
	v_lshrrev_b32_e32 v206, 2, v189
	v_and_b32_e32 v207, 3, v189
	v_bfe_u32 v208, v189, 4, 2
	v_xor_b32_e32 v207, v207, v208
	v_lshlrev_b32_e32 v207, 4, v207
	v_lshl_add_u32 v194, v206, 12, v207
	v_add_u32_e32 v195, 0xfc00, v194
	v_add_u32_e32 v196, 0x1f800, v194
	v_add_u32_e32 v197, 0x2f400, v194
	v_lshrrev_b32_e32 v206, 5, v189
	v_bfe_u32 v207, v80, 1, 3
	v_xor_b32_e32 v207, v207, v206
	v_lshlrev_b32_e32 v208, 3, v80
	v_or_b32_e32 v209, v208, v207
	v_lshl_add_u32 v198, v209, 4, s78
	v_xor_b32_e32 v210, 2, v207
	v_or_b32_e32 v210, v208, v210
	v_lshl_add_u32 v199, v210, 4, s78
	v_xor_b32_e32 v210, 4, v207
	v_or_b32_e32 v210, v208, v210
	v_lshl_add_u32 v200, v210, 4, s78
	v_xor_b32_e32 v210, 6, v207
	v_or_b32_e32 v210, v208, v210
	v_lshl_add_u32 v201, v210, 4, s78
	v_bfe_u32 v207, v82, 2, 2
	v_xor_b32_e32 v207, v207, v206
	v_lshlrev_b32_e32 v208, 2, v82
	v_or_b32_e32 v209, v208, v207
	v_lshl_add_u32 v202, v209, 4, s78
	v_add_u32_e32 v202, 0x1000, v202
	v_xor_b32_e32 v210, 2, v207
	v_or_b32_e32 v210, v208, v210
	v_lshl_add_u32 v203, v210, 4, s78
	v_add_u32_e32 v203, 0x1000, v203
	v_add_u32_e32 v204, 0x800, v202
	v_add_u32_e32 v205, 0x800, v203
	s_mul_i32 s44, s33, 48
	s_add_i32 s44, s44, 0xfffff000
	s_mov_b32 s101, 48
	s_cmpk_gt_u32 s33, 0xbf
	s_cbranch_scc1 .Latt_cls
	s_mul_i32 s44, s33, 40
	s_addk_i32 s44, 0xf600
	s_mov_b32 s101, 40

; #define ATT_LOAD(K_, V_, kb_) do { _Pragma("unroll") for (int ks = 0; ks < 4; ++ks) K_[ks] = *(const bf16x8_t*)(kbase + (size_t)(32 * (kb_)) * 1024 + 16 * ks); \
;         _Pragma("unroll") for (int i = 0; i < 4; ++i) V_[i] = *(const bf16x8_t*)(vbase + (size_t)(32 * (i >> 1)) * 2048 + 32 * (kb_) + 16 * (i & 1)); } while (0)
; __device__ __forceinline__ void attn_mfma(const Args& a, int u0, int ucnt, int ustride) {
;     ...
;     for (int uk = 0; uk < ucnt; ++uk) { const int u = u0 + uk * ustride;
;         const int qb = u & 63, bh = u >> 6, h = bh & 15, b = bh >> 4;
;         const size_t rowq = (size_t)b * SEQ + 32 * qb + r32;
;         bf16* qp = QS + rowq * 2048 + 1024 + 64 * h;
;         const bf16* kbase = SK + ((size_t)b * SEQ + kap) * 1024 + 64 * h + 8 * hi;
;         const bf16* vbase = VT + ((size_t)bh * 64 + r32) * 2048 + 8 * hi;
;         bf16x8_t Qf[4];
; #pragma unroll
;         for (int ks = 0; ks < 4; ++ks) Qf[ks] = *(const bf16x8_t*)(qp + 16 * ks + 8 * hi);
;         f32x16 O0, O1;
; #pragma unroll
;         for (int j = 0; j < 16; ++j) { O0[j] = 0.f; O1[j] = 0.f; }
;         float carry = 1.f;
;         bf16x8_t KA[4], VA[4], KB[4], VB[4];
;     ...
;         ATT_LOAD(KA, VA, qb);
;         int kb = qb;
;         ATT_LOAD(KB, VB, kb > 0 ? kb - 1 : 0);
.LBB0_401:
	s_mov_b64 s[98:99], exec
	s_mov_b64 exec, 1
	v_mov_b32_e32 v211, 0x2670c
	v_mov_b32_e32 v212, 1
	ds_add_rtn_u32 v213, v211, v212
	s_mov_b64 exec, s[98:99]
	s_waitcnt lgkmcnt(0)
	v_readfirstlane_b32 s40, v213
	s_cmp_ge_u32 s40, s101
	s_cbranch_scc1 .LBB0_407
	s_add_i32 s40, s44, s40
	s_ashr_i32 s48, s40, 10
	s_and_b32 s47, s40, 63
	s_ashr_i32 s49, s48, 31
	s_lshl_b64 s[48:49], s[48:49], 11
	s_lshl_b32 s43, s47, 5
	s_or_b32 s43, s48, s43
	v_mov_b32_e32 v1, s49
	v_or_b32_e32 v0, s43, v82
	s_ashr_i32 s42, s40, 6
	v_lshlrev_b64 v[0:1], 12, v[0:1]
	s_and_b32 s40, s40, 0x3c0
	v_lshl_add_u64 v[0:1], s[72:73], 0, v[0:1]
	s_lshl_b32 s40, s40, 1
	v_lshl_add_u64 v[0:1], v[0:1], 0, s[40:41]
	s_mov_b64 s[76:77], 0x4b00800
	v_lshl_add_u64 v[90:91], v[0:1], 0, s[76:77]
	v_mov_b32_e32 v1, s49
	v_or_b32_e32 v0, s48, v80
	v_lshlrev_b64 v[0:1], 11, v[0:1]
	v_lshl_add_u64 v[0:1], s[90:91], 0, v[0:1]
	v_lshl_add_u64 v[0:1], v[0:1], 0, s[40:41]
	v_lshl_add_u64 v[92:93], v[0:1], 0, v[88:89]
	s_lshl_b32 s94, s48, 11
	s_add_u32 s80, s90, s94
	s_addc_u32 s81, s91, 0
	s_add_u32 s80, s80, s40
	s_addc_u32 s81, s81, 0
	s_lshl_b32 s94, s42, 18
	s_add_u32 s82, s92, s94
	s_addc_u32 s83, s93, 0
	v_lshl_add_u64 v[2:3], v[90:91], 0, v[88:89]
	global_load_dwordx4 v[48:51], v[2:3], off
	global_load_dwordx4 v[52:55], v[2:3], off offset:32
	global_load_dwordx4 v[56:59], v[2:3], off offset:64
	global_load_dwordx4 v[60:63], v[2:3], off offset:96
	s_lshl_b32 s94, s47, 16
	s_add_u32 s94, s80, s94
	s_addc_u32 s95, s81, 0
	s_lshl_b32 s96, s47, 6
	s_add_u32 s96, s82, s96
	s_addc_u32 s97, s83, 0
	s_add_i32 m0, s78, 0x0
	s_nop 0
	global_load_lds_dwordx4 v190, s[94:95]
	global_load_lds_dwordx4 v191, s[94:95] offset:1024
	global_load_lds_dwordx4 v192, s[94:95] offset:2048
	global_load_lds_dwordx4 v193, s[94:95] offset:3072
	s_add_i32 m0, s78, 0x1000
	s_nop 0
	global_load_lds_dwordx4 v194, s[96:97]
	global_load_lds_dwordx4 v195, s[96:97] offset:1024
	global_load_lds_dwordx4 v196, s[96:97] offset:2048
	global_load_lds_dwordx4 v197, s[96:97] offset:3072
	s_add_i32 s98, s47, -1
	s_max_i32 s98, s98, 0
	s_lshl_b32 s94, s98, 16
	s_add_u32 s94, s80, s94
	s_addc_u32 s95, s81, 0
	s_lshl_b32 s96, s98, 6
	s_add_u32 s96, s82, s96
	s_addc_u32 s97, s83, 0
	s_add_i32 m0, s78, 0x2000
	s_nop 0
	global_load_lds_dwordx4 v190, s[94:95]
	global_load_lds_dwordx4 v191, s[94:95] offset:1024
	global_load_lds_dwordx4 v192, s[94:95] offset:2048
	global_load_lds_dwordx4 v193, s[94:95] offset:3072
	s_add_i32 m0, s78, 0x3000
	s_nop 0
	global_load_lds_dwordx4 v194, s[96:97]
	global_load_lds_dwordx4 v195, s[96:97] offset:1024
	global_load_lds_dwordx4 v196, s[96:97] offset:2048
	global_load_lds_dwordx4 v197, s[96:97] offset:3072
	s_waitcnt vmcnt(8)
	ds_read_b128 v[0:3], v198
	ds_read_b128 v[28:31], v199
	ds_read_b128 v[36:39], v200
	ds_read_b128 v[40:43], v201
	ds_read_b128 v[24:27], v202
	ds_read_b128 v[20:23], v203
	ds_read_b128 v[16:19], v204
	ds_read_b128 v[32:35], v205
	s_waitcnt lgkmcnt(7)
	v_mfma_f32_32x32x16_bf16 v[0:15], v[0:3], v[48:51], 0
	s_waitcnt lgkmcnt(6)
	v_mfma_f32_32x32x16_bf16 v[0:15], v[28:31], v[52:55], v[0:15]
	s_waitcnt lgkmcnt(5)
	v_mfma_f32_32x32x16_bf16 v[0:15], v[36:39], v[56:59], v[0:15]
	s_waitcnt lgkmcnt(4)
; __device__ __forceinline__ unsigned cvtpk(float lo, float hi) { const f32x2_t v = {lo, hi}; return __builtin_bit_cast(unsigned, __builtin_convertvector(v, bf16x2_cv)); }
; #define MFMA32(A, B, C) __builtin_amdgcn_mfma_f32_32x32x16_bf16((A), (B), (C), 0, 0, 0)
; template <bool DIAG> __device__ __forceinline__ bool attn_tile(const bf16x8_t (&Kc)[4], const bf16x8_t (&Vc)[4], const bf16x8_t (&Qf)[4], f32x16& O0, f32x16& O1, float& carry, int r32, int hi) {
;     ...
;     float kp[16], sg[16];
; #pragma unroll
;     for (int j = 0; j < 16; ++j) {
;         const float r = __builtin_amdgcn_rcpf(1.0f + __builtin_amdgcn_exp2f(Sx[j]));
;         if (DIAG) { const int sl = 16 * (j >> 3) + 8 * hi + (j & 7); const bool valid = sl < r32; kp[j] = valid ? r : 1.f; sg[j] = valid ? 1.0f - r : 0.f; }
;         else { kp[j] = r; sg[j] = 1.0f - r; }
;     }
; #pragma unroll
;     for (int j = 6; j >= 0; --j) { sg[j] *= kp[j + 1]; kp[j] *= kp[j + 1]; sg[8 + j] *= kp[8 + j + 1]; kp[8 + j] *= kp[8 + j + 1]; }
;     const float G0 = kp[0], G1 = kp[8];
;     const float P0 = __shfl_xor(G0, 32), P1 = __shfl_xor(G1, 32);
;     const float after0 = (hi == 0 ? P0 : 1.f) * P1 * G1 * carry, after1 = (hi == 0 ? P1 : 1.f) * carry;
; #pragma unroll
;     for (int j = 0; j < 16; ++j) sg[j] *= (j < 8 ? after0 : after1);
;     carry *= (G0 * G1) * (P0 * P1);
;     v4u w0, w1; w0.x = cvtpk(sg[0], sg[1]); w0.y = cvtpk(sg[2], sg[3]); w0.z = cvtpk(sg[4], sg[5]); w0.w = cvtpk(sg[6], sg[7]);
;     w1.x = cvtpk(sg[8], sg[9]); w1.y = cvtpk(sg[10], sg[11]); w1.z = cvtpk(sg[12], sg[13]); w1.w = cvtpk(sg[14], sg[15]);
;     const bf16x8_t Pb0 = __builtin_bit_cast(bf16x8_t, w0), Pb1 = __builtin_bit_cast(bf16x8_t, w1);
;     O0 = MFMA32(Vc[0], Pb0, O0); O0 = MFMA32(Vc[1], Pb1, O0);
;     O1 = MFMA32(Vc[2], Pb0, O1); O1 = MFMA32(Vc[3], Pb1, O1);
;     return __all(carry < 0x1p-134f);
	v_mfma_f32_32x32x16_bf16 v[0:15], v[40:43], v[60:63], v[0:15]
	s_nop 11
	v_exp_f32_e32 v2, v2
	v_exp_f32_e32 v0, v0
	v_exp_f32_e32 v1, v1
	v_add_f32_e32 v2, 1.0, v2
	v_rcp_f32_e32 v28, v2
	v_exp_f32_e32 v2, v3
	v_exp_f32_e32 v3, v7
	v_exp_f32_e32 v7, v15
	v_add_f32_e32 v0, 1.0, v0
	v_add_f32_e32 v2, 1.0, v2
	v_rcp_f32_e32 v29, v2
	v_exp_f32_e32 v2, v4
	v_add_f32_e32 v7, 1.0, v7
	v_rcp_f32_e32 v7, v7
	v_add_f32_e32 v3, 1.0, v3
	v_add_f32_e32 v2, 1.0, v2
	v_rcp_f32_e32 v4, v2
	v_exp_f32_e32 v2, v5
	v_rcp_f32_e32 v3, v3
	v_add_f32_e32 v1, 1.0, v1
	v_rcp_f32_e32 v0, v0
	v_add_f32_e32 v2, 1.0, v2
	v_rcp_f32_e32 v5, v2
	v_exp_f32_e32 v2, v6
	v_exp_f32_e32 v6, v8
	v_cndmask_b32_e64 v37, 1.0, v3, s[16:17]
	v_rcp_f32_e32 v1, v1
	v_add_f32_e32 v2, 1.0, v2
	v_add_f32_e32 v6, 1.0, v6
	v_rcp_f32_e32 v8, v6
	v_exp_f32_e32 v6, v9
	v_rcp_f32_e32 v2, v2
	v_sub_f32_e32 v3, 1.0, v3
	v_cndmask_b32_e64 v3, 0, v3, s[16:17]
	v_add_f32_e32 v6, 1.0, v6
	v_rcp_f32_e32 v9, v6
	v_exp_f32_e32 v6, v10
	v_cndmask_b32_e64 v36, 1.0, v2, s[14:15]
	v_sub_f32_e32 v2, 1.0, v2
	v_cndmask_b32_e64 v2, 0, v2, s[14:15]
	v_add_f32_e32 v6, 1.0, v6
	v_rcp_f32_e32 v30, v6
	v_exp_f32_e32 v6, v11
	v_mul_f32_e32 v2, v37, v2
	v_mul_f32_e32 v37, v36, v37
	v_cndmask_b32_e64 v39, 1.0, v30, s[24:25]
	v_add_f32_e32 v6, 1.0, v6
	v_rcp_f32_e32 v31, v6
	v_exp_f32_e32 v6, v12
	s_nop 0
	v_add_f32_e32 v6, 1.0, v6
	v_rcp_f32_e32 v10, v6
	v_exp_f32_e32 v6, v13
	v_cndmask_b32_e64 v13, 1.0, v7, s[34:35]
	v_sub_f32_e32 v7, 1.0, v7
	v_cndmask_b32_e64 v38, 1.0, v10, s[28:29]
	v_add_f32_e32 v6, 1.0, v6
	v_rcp_f32_e32 v11, v6
	v_exp_f32_e32 v6, v14
	v_cndmask_b32_e64 v7, 0, v7, s[34:35]
	v_cndmask_b32_e64 v14, 1.0, v11, s[26:27]
	v_add_f32_e32 v6, 1.0, v6
	v_rcp_f32_e32 v6, v6
	v_pk_add_f32 v[10:11], v[10:11], 1.0 op_sel_hi:[1,0] neg_lo:[1,0] neg_hi:[1,0]
	v_cndmask_b32_e64 v12, 1.0, v6, s[30:31]
	v_sub_f32_e32 v6, 1.0, v6
	v_cndmask_b32_e64 v6, 0, v6, s[30:31]
	v_mul_f32_e32 v6, v13, v6
	v_mul_f32_e32 v13, v12, v13
	v_cndmask_b32_e64 v11, 0, v11, s[26:27]
	v_cndmask_b32_e64 v10, 0, v10, s[28:29]
	v_mul_f32_e32 v12, v14, v13
	v_pk_mul_f32 v[10:11], v[10:11], v[12:13]
	v_cndmask_b32_e64 v13, 1.0, v31, s[22:23]
	v_pk_add_f32 v[14:15], v[30:31], 1.0 op_sel_hi:[1,0] neg_lo:[1,0] neg_hi:[1,0]
	v_mul_f32_e32 v31, v38, v12
	v_cndmask_b32_e64 v15, 0, v15, s[22:23]
	v_cndmask_b32_e64 v14, 0, v14, s[24:25]
	v_mul_f32_e32 v30, v13, v31
	v_pk_mul_f32 v[12:13], v[14:15], v[30:31]
	v_cndmask_b32_e64 v38, 1.0, v8, s[20:21]
	v_cndmask_b32_e64 v14, 1.0, v9, s[18:19]
	v_pk_add_f32 v[8:9], v[8:9], 1.0 op_sel_hi:[1,0] neg_lo:[1,0] neg_hi:[1,0]
	v_mul_f32_e32 v15, v39, v30
	v_cndmask_b32_e64 v9, 0, v9, s[18:19]
	v_cndmask_b32_e64 v8, 0, v8, s[20:21]
	v_mul_f32_e32 v14, v14, v15
	v_pk_mul_f32 v[30:31], v[8:9], v[14:15]
	v_mul_f32_e32 v9, v38, v14
	v_cndmask_b32_e64 v15, 1.0, v4, s[12:13]
	v_cndmask_b32_e64 v38, 1.0, v5, s[10:11]
	v_pk_add_f32 v[4:5], v[4:5], 1.0 op_sel_hi:[1,0] neg_lo:[1,0] neg_hi:[1,0]
	v_mul_f32_e32 v36, v38, v37
	v_cndmask_b32_e64 v5, 0, v5, s[10:11]
	v_cndmask_b32_e64 v4, 0, v4, s[12:13]
	v_pk_mul_f32 v[4:5], v[4:5], v[36:37]
	v_cndmask_b32_e64 v38, 1.0, v28, s[8:9]
	v_cndmask_b32_e64 v39, 1.0, v29, s[6:7]
	v_pk_add_f32 v[28:29], v[28:29], 1.0 op_sel_hi:[1,0] neg_lo:[1,0] neg_hi:[1,0]
	v_mul_f32_e32 v37, v15, v36
	v_cndmask_b32_e64 v29, 0, v29, s[6:7]
	v_cndmask_b32_e64 v28, 0, v28, s[8:9]
	v_mul_f32_e32 v36, v39, v37
	v_pk_mul_f32 v[28:29], v[28:29], v[36:37]
	v_cndmask_b32_e64 v15, 1.0, v0, s[2:3]
	v_cndmask_b32_e64 v39, 1.0, v1, s[4:5]
	v_pk_add_f32 v[0:1], v[0:1], 1.0 op_sel_hi:[1,0] neg_lo:[1,0] neg_hi:[1,0]
	v_mul_f32_e32 v37, v38, v36
	v_cndmask_b32_e64 v1, 0, v1, s[4:5]
	v_cndmask_b32_e64 v0, 0, v0, s[2:3]
	v_mul_f32_e32 v36, v39, v37
	v_pk_mul_f32 v[0:1], v[0:1], v[36:37]
	v_mul_f32_e32 v37, v15, v36
	ds_bpermute_b32 v36, v81, v37
	ds_bpermute_b32 v8, v81, v9
	s_waitcnt lgkmcnt(0)
	v_cndmask_b32_e64 v15, 1.0, v36, s[36:37]
	v_mul_f32_e32 v15, v15, v8
	v_mul_f32_e32 v38, v15, v9
	v_cndmask_b32_e64 v14, 1.0, v8, s[36:37]
	v_pk_mul_f32 v[0:1], v[0:1], v[38:39] op_sel_hi:[1,0]
	v_pk_mul_f32 v[40:41], v[28:29], v[38:39] op_sel_hi:[1,0]
	v_pk_mul_f32 v[4:5], v[4:5], v[38:39] op_sel_hi:[1,0]
	v_pk_mul_f32 v[2:3], v[2:3], v[38:39] op_sel_hi:[1,0]
	v_pk_mul_f32 v[38:39], v[14:15], v[30:31] op_sel_hi:[0,1]
	v_pk_mul_f32 v[12:13], v[14:15], v[12:13] op_sel_hi:[0,1]
	v_pk_mul_f32 v[10:11], v[14:15], v[10:11] op_sel_hi:[0,1]
	v_pk_mul_f32 v[6:7], v[14:15], v[6:7] op_sel_hi:[0,1]
	v_pk_mul_f32 v[8:9], v[36:37], v[8:9]
	v_cvt_pk_bf16_f32 v28, v0, v1
	v_cvt_pk_bf16_f32 v29, v40, v41
	v_cvt_pk_bf16_f32 v30, v4, v5
	v_cvt_pk_bf16_f32 v31, v2, v3
	v_mul_f32_e32 v97, v8, v9
	v_cvt_pk_bf16_f32 v36, v38, v39
	v_cvt_pk_bf16_f32 v37, v12, v13
	v_cvt_pk_bf16_f32 v38, v10, v11
	v_cvt_pk_bf16_f32 v39, v6, v7
	s_nop 0
	v_mfma_f32_32x32x16_bf16 v[0:15], v[24:27], v[28:31], 0
	v_cmp_gt_f32_e32 vcc, s45, v97
	s_cmp_eq_u64 vcc, exec
	s_cselect_b64 s[42:43], -1, 0
	s_cmp_eq_u32 s47, 0
	s_cselect_b64 s[48:49], -1, 0
	s_or_b64 s[42:43], s[48:49], s[42:43]
	s_and_b64 vcc, exec, s[42:43]
	s_nop 0
	v_mfma_f32_32x32x16_bf16 v[0:15], v[20:23], v[36:39], v[0:15]
	s_nop 0
	v_mfma_f32_32x32x16_bf16 v[16:31], v[16:19], v[28:31], 0
	s_nop 0
	v_mfma_f32_32x32x16_bf16 v[16:31], v[32:35], v[36:39], v[16:31]
	s_cbranch_vccnz .LBB0_400
	s_add_i32 s47, s47, -1
